# v57 + P5 EpiUp uses v_pk_mul_f32 for the rstd scaling and the square (128 fewer VALU ops per wave per unit, same arithmetic)
# baseline (speedup 1.0000x reference)
; __device__ __forceinline__ u32x4 pack8(const f32x4 a, const f32x4 b) { u32x4 w; w.x = cvt_pk_bf16(a[0], a[1]); w.y = cvt_pk_bf16(a[2], a[3]); w.z = cvt_pk_bf16(b[0], b[1]); w.w = cvt_pk_bf16(b[2], b[3]); return w; }
;     __device__ __forceinline__ void operator()(const f32x4 (&acc)[2][2][4][2], const Unit& u, int wr, int wc, int fr, int fq) const {
;     ...
;             for (int m = 0; m < 4; ++m) { const int row = rbase + ai * 128 + m * 16; const f32x4* sp = (const f32x4*)(SSP + (size_t)row * 16);
;                 const f32x4 s4 = (sp[0] + sp[1]) + (sp[2] + sp[3]); const float rstd = __builtin_amdgcn_rsqf(((s4[0] + s4[1]) + (s4[2] + s4[3])) * (1.0f / 1024.0f) + EPS);
; #pragma unroll
;                 for (int bj = 0; bj < 2; ++bj) { f32x4 v0 = acc[ai][bj][m][0] * rstd, v1 = acc[ai][bj][m][1] * rstd;
; #pragma unroll
;                     for (int i = 0; i < 4; ++i) { const float a = fmaxf(v0[i], 0.f), b = fmaxf(v1[i], 0.f); v0[i] = a * a; v1[i] = b * b; }
;                     *(u32x4*)(Z + (size_t)row * FF + cb + bj * 128) = pack8(v0, v1); }
.LBB0_1543:
	v_lshlrev_b64 v[220:221], 13, v[146:147]
	v_lshl_or_b32 v222, s60, 8, v150
	v_ashrrev_i32_e32 v223, 31, v222
	v_lshlrev_b64 v[222:223], 1, v[222:223]
	v_lshl_add_u64 v[220:221], s[8:9], 0, v[220:221]
	v_lshl_add_u64 v[220:221], v[220:221], 0, v[222:223]
	s_mov_b64 s[100:101], 0xa0000
	s_mov_b64 s[98:99], 0x20000
	s_waitcnt vmcnt(4)
	v_pk_add_f32 v[156:157], v[156:157], v[158:159]
	v_pk_add_f32 v[160:161], v[160:161], v[162:163]
	v_pk_add_f32 v[164:165], v[164:165], v[166:167]
	v_pk_add_f32 v[168:169], v[168:169], v[170:171]
	v_add_f32_e32 v156, v156, v157
	v_add_f32_e32 v160, v160, v161
	v_add_f32_e32 v164, v164, v165
	v_add_f32_e32 v168, v168, v169
	v_mov_b32_e32 v157, v156
	v_mov_b32_e32 v161, v160
	v_mov_b32_e32 v165, v164
	v_mov_b32_e32 v169, v168
	s_nop 1
	v_permlane16_swap_b32_e32 v157, v156
	v_permlane16_swap_b32_e32 v161, v160
	v_permlane16_swap_b32_e32 v165, v164
	v_permlane16_swap_b32_e32 v169, v168
	s_nop 1
	v_add_f32_e32 v156, v156, v157
	v_add_f32_e32 v160, v160, v161
	v_add_f32_e32 v164, v164, v165
	v_add_f32_e32 v168, v168, v169
	v_mov_b32_e32 v157, v156
	v_mov_b32_e32 v161, v160
	v_mov_b32_e32 v165, v164
	v_mov_b32_e32 v169, v168
	s_nop 1
	v_permlane32_swap_b32_e32 v157, v156
	v_permlane32_swap_b32_e32 v161, v160
	v_permlane32_swap_b32_e32 v165, v164
	v_permlane32_swap_b32_e32 v169, v168
	s_nop 1
	v_add_f32_e32 v156, v156, v157
	v_add_f32_e32 v160, v160, v161
	v_add_f32_e32 v164, v164, v165
	v_add_f32_e32 v168, v168, v169
	v_fmamk_f32 v156, v156, 0x3a800000, v154
	v_fmamk_f32 v160, v160, 0x3a800000, v154
	v_fmamk_f32 v164, v164, 0x3a800000, v154
	v_fmamk_f32 v168, v168, 0x3a800000, v154
	v_rsq_f32_e32 v156, v156
	v_rsq_f32_e32 v160, v160
	v_rsq_f32_e32 v164, v164
	v_rsq_f32_e32 v168, v168
	s_nop 0
	v_pk_mul_f32 v[112:113], v[112:113], v[156:157] op_sel_hi:[1,0]
	v_pk_mul_f32 v[114:115], v[114:115], v[156:157] op_sel_hi:[1,0]
	v_pk_mul_f32 v[116:117], v[116:117], v[156:157] op_sel_hi:[1,0]
	v_pk_mul_f32 v[118:119], v[118:119], v[156:157] op_sel_hi:[1,0]
	v_pk_mul_f32 v[120:121], v[120:121], v[156:157] op_sel_hi:[1,0]
	v_pk_mul_f32 v[122:123], v[122:123], v[156:157] op_sel_hi:[1,0]
	v_pk_mul_f32 v[124:125], v[124:125], v[156:157] op_sel_hi:[1,0]
	v_pk_mul_f32 v[126:127], v[126:127], v[156:157] op_sel_hi:[1,0]
	v_max_f32_e32 v112, 0, v112
	v_max_f32_e32 v113, 0, v113
	v_max_f32_e32 v114, 0, v114
	v_max_f32_e32 v115, 0, v115
	v_max_f32_e32 v116, 0, v116
	v_max_f32_e32 v117, 0, v117
	v_max_f32_e32 v118, 0, v118
	v_max_f32_e32 v119, 0, v119
	v_max_f32_e32 v120, 0, v120
	v_max_f32_e32 v121, 0, v121
	v_max_f32_e32 v122, 0, v122
	v_max_f32_e32 v123, 0, v123
	v_max_f32_e32 v124, 0, v124
	v_max_f32_e32 v125, 0, v125
	v_max_f32_e32 v126, 0, v126
	v_max_f32_e32 v127, 0, v127
	v_pk_mul_f32 v[112:113], v[112:113], v[112:113]
	v_pk_mul_f32 v[114:115], v[114:115], v[114:115]
	v_pk_mul_f32 v[116:117], v[116:117], v[116:117]
	v_pk_mul_f32 v[118:119], v[118:119], v[118:119]
	v_pk_mul_f32 v[120:121], v[120:121], v[120:121]
	v_pk_mul_f32 v[122:123], v[122:123], v[122:123]
	v_pk_mul_f32 v[124:125], v[124:125], v[124:125]
	v_pk_mul_f32 v[126:127], v[126:127], v[126:127]
	v_cvt_pk_bf16_f32 v124, v124, v125
	v_cvt_pk_bf16_f32 v125, v126, v127
	v_cvt_pk_bf16_f32 v126, v120, v121
	v_cvt_pk_bf16_f32 v127, v122, v123
	v_cvt_pk_bf16_f32 v116, v116, v117
	v_cvt_pk_bf16_f32 v117, v118, v119
	v_cvt_pk_bf16_f32 v118, v112, v113
	v_cvt_pk_bf16_f32 v119, v114, v115
	global_store_dwordx4 v[220:221], v[124:127], off
	global_store_dwordx4 v[220:221], v[116:119], off offset:256
	v_lshl_add_u64 v[220:221], v[220:221], 0, s[98:99]
	v_pk_mul_f32 v[96:97], v[96:97], v[160:161] op_sel_hi:[1,0]
	v_pk_mul_f32 v[98:99], v[98:99], v[160:161] op_sel_hi:[1,0]
	v_pk_mul_f32 v[100:101], v[100:101], v[160:161] op_sel_hi:[1,0]
	v_pk_mul_f32 v[102:103], v[102:103], v[160:161] op_sel_hi:[1,0]
	v_pk_mul_f32 v[104:105], v[104:105], v[160:161] op_sel_hi:[1,0]
	v_pk_mul_f32 v[106:107], v[106:107], v[160:161] op_sel_hi:[1,0]
	v_pk_mul_f32 v[108:109], v[108:109], v[160:161] op_sel_hi:[1,0]
	v_pk_mul_f32 v[110:111], v[110:111], v[160:161] op_sel_hi:[1,0]
	v_max_f32_e32 v96, 0, v96
	v_max_f32_e32 v97, 0, v97
	v_max_f32_e32 v98, 0, v98
	v_max_f32_e32 v99, 0, v99
	v_max_f32_e32 v100, 0, v100
	v_max_f32_e32 v101, 0, v101
	v_max_f32_e32 v102, 0, v102
	v_max_f32_e32 v103, 0, v103
	v_max_f32_e32 v104, 0, v104
	v_max_f32_e32 v105, 0, v105
	v_max_f32_e32 v106, 0, v106
	v_max_f32_e32 v107, 0, v107
	v_max_f32_e32 v108, 0, v108
	v_max_f32_e32 v109, 0, v109
	v_max_f32_e32 v110, 0, v110
	v_max_f32_e32 v111, 0, v111
	v_pk_mul_f32 v[96:97], v[96:97], v[96:97]
	v_pk_mul_f32 v[98:99], v[98:99], v[98:99]
	v_pk_mul_f32 v[100:101], v[100:101], v[100:101]
	v_pk_mul_f32 v[102:103], v[102:103], v[102:103]
	v_pk_mul_f32 v[104:105], v[104:105], v[104:105]
	v_pk_mul_f32 v[106:107], v[106:107], v[106:107]
	v_pk_mul_f32 v[108:109], v[108:109], v[108:109]
	v_pk_mul_f32 v[110:111], v[110:111], v[110:111]
	v_cvt_pk_bf16_f32 v108, v108, v109
	v_cvt_pk_bf16_f32 v109, v110, v111
	v_cvt_pk_bf16_f32 v110, v104, v105
	v_cvt_pk_bf16_f32 v111, v106, v107
	v_cvt_pk_bf16_f32 v100, v100, v101
	v_cvt_pk_bf16_f32 v101, v102, v103
	v_cvt_pk_bf16_f32 v102, v96, v97
	v_cvt_pk_bf16_f32 v103, v98, v99
	global_store_dwordx4 v[220:221], v[108:111], off
	global_store_dwordx4 v[220:221], v[100:103], off offset:256
	v_lshl_add_u64 v[220:221], v[220:221], 0, s[98:99]
	v_pk_mul_f32 v[80:81], v[80:81], v[164:165] op_sel_hi:[1,0]
	v_pk_mul_f32 v[82:83], v[82:83], v[164:165] op_sel_hi:[1,0]
	v_pk_mul_f32 v[84:85], v[84:85], v[164:165] op_sel_hi:[1,0]
	v_pk_mul_f32 v[86:87], v[86:87], v[164:165] op_sel_hi:[1,0]
; __device__ __forceinline__ u32x4 pack8(const f32x4 a, const f32x4 b) { u32x4 w; w.x = cvt_pk_bf16(a[0], a[1]); w.y = cvt_pk_bf16(a[2], a[3]); w.z = cvt_pk_bf16(b[0], b[1]); w.w = cvt_pk_bf16(b[2], b[3]); return w; }
;     __device__ __forceinline__ void operator()(const f32x4 (&acc)[2][2][4][2], const Unit& u, int wr, int wc, int fr, int fq) const {
;     ...
;             for (int m = 0; m < 4; ++m) { const int row = rbase + ai * 128 + m * 16; const f32x4* sp = (const f32x4*)(SSP + (size_t)row * 16);
;                 const f32x4 s4 = (sp[0] + sp[1]) + (sp[2] + sp[3]); const float rstd = __builtin_amdgcn_rsqf(((s4[0] + s4[1]) + (s4[2] + s4[3])) * (1.0f / 1024.0f) + EPS);
; #pragma unroll
;                 for (int bj = 0; bj < 2; ++bj) { f32x4 v0 = acc[ai][bj][m][0] * rstd, v1 = acc[ai][bj][m][1] * rstd;
; #pragma unroll
;                     for (int i = 0; i < 4; ++i) { const float a = fmaxf(v0[i], 0.f), b = fmaxf(v1[i], 0.f); v0[i] = a * a; v1[i] = b * b; }
;                     *(u32x4*)(Z + (size_t)row * FF + cb + bj * 128) = pack8(v0, v1); }
	v_pk_mul_f32 v[88:89], v[88:89], v[164:165] op_sel_hi:[1,0]
	v_pk_mul_f32 v[90:91], v[90:91], v[164:165] op_sel_hi:[1,0]
	v_pk_mul_f32 v[92:93], v[92:93], v[164:165] op_sel_hi:[1,0]
	v_pk_mul_f32 v[94:95], v[94:95], v[164:165] op_sel_hi:[1,0]
	v_max_f32_e32 v80, 0, v80
	v_max_f32_e32 v81, 0, v81
	v_max_f32_e32 v82, 0, v82
	v_max_f32_e32 v83, 0, v83
	v_max_f32_e32 v84, 0, v84
	v_max_f32_e32 v85, 0, v85
	v_max_f32_e32 v86, 0, v86
	v_max_f32_e32 v87, 0, v87
	v_max_f32_e32 v88, 0, v88
	v_max_f32_e32 v89, 0, v89
	v_max_f32_e32 v90, 0, v90
	v_max_f32_e32 v91, 0, v91
	v_max_f32_e32 v92, 0, v92
	v_max_f32_e32 v93, 0, v93
	v_max_f32_e32 v94, 0, v94
	v_max_f32_e32 v95, 0, v95
	v_pk_mul_f32 v[80:81], v[80:81], v[80:81]
	v_pk_mul_f32 v[82:83], v[82:83], v[82:83]
	v_pk_mul_f32 v[84:85], v[84:85], v[84:85]
	v_pk_mul_f32 v[86:87], v[86:87], v[86:87]
	v_pk_mul_f32 v[88:89], v[88:89], v[88:89]
	v_pk_mul_f32 v[90:91], v[90:91], v[90:91]
	v_pk_mul_f32 v[92:93], v[92:93], v[92:93]
	v_pk_mul_f32 v[94:95], v[94:95], v[94:95]
	v_cvt_pk_bf16_f32 v92, v92, v93
	v_cvt_pk_bf16_f32 v93, v94, v95
	v_cvt_pk_bf16_f32 v94, v88, v89
	v_cvt_pk_bf16_f32 v95, v90, v91
	v_cvt_pk_bf16_f32 v84, v84, v85
	v_cvt_pk_bf16_f32 v85, v86, v87
	v_cvt_pk_bf16_f32 v86, v80, v81
	v_cvt_pk_bf16_f32 v87, v82, v83
	global_store_dwordx4 v[220:221], v[92:95], off
	global_store_dwordx4 v[220:221], v[84:87], off offset:256
	v_lshl_add_u64 v[220:221], v[220:221], 0, s[98:99]
	v_pk_mul_f32 v[64:65], v[64:65], v[168:169] op_sel_hi:[1,0]
	v_pk_mul_f32 v[66:67], v[66:67], v[168:169] op_sel_hi:[1,0]
	v_pk_mul_f32 v[68:69], v[68:69], v[168:169] op_sel_hi:[1,0]
	v_pk_mul_f32 v[70:71], v[70:71], v[168:169] op_sel_hi:[1,0]
	v_pk_mul_f32 v[72:73], v[72:73], v[168:169] op_sel_hi:[1,0]
	v_pk_mul_f32 v[74:75], v[74:75], v[168:169] op_sel_hi:[1,0]
	v_pk_mul_f32 v[76:77], v[76:77], v[168:169] op_sel_hi:[1,0]
	v_pk_mul_f32 v[78:79], v[78:79], v[168:169] op_sel_hi:[1,0]
	v_max_f32_e32 v64, 0, v64
	v_max_f32_e32 v65, 0, v65
	v_max_f32_e32 v66, 0, v66
	v_max_f32_e32 v67, 0, v67
	v_max_f32_e32 v68, 0, v68
	v_max_f32_e32 v69, 0, v69
	v_max_f32_e32 v70, 0, v70
	v_max_f32_e32 v71, 0, v71
	v_max_f32_e32 v72, 0, v72
	v_max_f32_e32 v73, 0, v73
	v_max_f32_e32 v74, 0, v74
	v_max_f32_e32 v75, 0, v75
	v_max_f32_e32 v76, 0, v76
	v_max_f32_e32 v77, 0, v77
	v_max_f32_e32 v78, 0, v78
	v_max_f32_e32 v79, 0, v79
	v_pk_mul_f32 v[64:65], v[64:65], v[64:65]
	v_pk_mul_f32 v[66:67], v[66:67], v[66:67]
	v_pk_mul_f32 v[68:69], v[68:69], v[68:69]
	v_pk_mul_f32 v[70:71], v[70:71], v[70:71]
	v_pk_mul_f32 v[72:73], v[72:73], v[72:73]
	v_pk_mul_f32 v[74:75], v[74:75], v[74:75]
	v_pk_mul_f32 v[76:77], v[76:77], v[76:77]
	v_pk_mul_f32 v[78:79], v[78:79], v[78:79]
	v_cvt_pk_bf16_f32 v76, v76, v77
	v_cvt_pk_bf16_f32 v77, v78, v79
	v_cvt_pk_bf16_f32 v78, v72, v73
	v_cvt_pk_bf16_f32 v79, v74, v75
	v_cvt_pk_bf16_f32 v68, v68, v69
	v_cvt_pk_bf16_f32 v69, v70, v71
	v_cvt_pk_bf16_f32 v70, v64, v65
	v_cvt_pk_bf16_f32 v71, v66, v67
	global_store_dwordx4 v[220:221], v[76:79], off
	global_store_dwordx4 v[220:221], v[68:71], off offset:256
	v_lshl_add_u64 v[220:221], v[220:221], 0, s[100:101]
	s_waitcnt vmcnt(8)
	v_pk_add_f32 v[172:173], v[172:173], v[174:175]
	v_pk_add_f32 v[176:177], v[176:177], v[178:179]
	v_pk_add_f32 v[180:181], v[180:181], v[182:183]
	v_pk_add_f32 v[184:185], v[184:185], v[186:187]
	v_add_f32_e32 v172, v172, v173
	v_add_f32_e32 v176, v176, v177
	v_add_f32_e32 v180, v180, v181
	v_add_f32_e32 v184, v184, v185
	v_mov_b32_e32 v173, v172
	v_mov_b32_e32 v177, v176
	v_mov_b32_e32 v181, v180
	v_mov_b32_e32 v185, v184
	s_nop 1
	v_permlane16_swap_b32_e32 v173, v172
	v_permlane16_swap_b32_e32 v177, v176
	v_permlane16_swap_b32_e32 v181, v180
	v_permlane16_swap_b32_e32 v185, v184
	s_nop 1
	v_add_f32_e32 v172, v172, v173
	v_add_f32_e32 v176, v176, v177
	v_add_f32_e32 v180, v180, v181
	v_add_f32_e32 v184, v184, v185
	v_mov_b32_e32 v173, v172
	v_mov_b32_e32 v177, v176
	v_mov_b32_e32 v181, v180
	v_mov_b32_e32 v185, v184
	s_nop 1
	v_permlane32_swap_b32_e32 v173, v172
	v_permlane32_swap_b32_e32 v177, v176
	v_permlane32_swap_b32_e32 v181, v180
	v_permlane32_swap_b32_e32 v185, v184
	s_nop 1
	v_add_f32_e32 v172, v172, v173
	v_add_f32_e32 v176, v176, v177
	v_add_f32_e32 v180, v180, v181
	v_add_f32_e32 v184, v184, v185
	v_fmamk_f32 v172, v172, 0x3a800000, v154
	v_fmamk_f32 v176, v176, 0x3a800000, v154
	v_fmamk_f32 v180, v180, 0x3a800000, v154
	v_fmamk_f32 v184, v184, 0x3a800000, v154
	v_rsq_f32_e32 v172, v172
	v_rsq_f32_e32 v176, v176
	v_rsq_f32_e32 v180, v180
	v_rsq_f32_e32 v184, v184
	s_nop 0
	v_pk_mul_f32 v[48:49], v[48:49], v[172:173] op_sel_hi:[1,0]
	v_pk_mul_f32 v[50:51], v[50:51], v[172:173] op_sel_hi:[1,0]
	v_pk_mul_f32 v[52:53], v[52:53], v[172:173] op_sel_hi:[1,0]
	v_pk_mul_f32 v[54:55], v[54:55], v[172:173] op_sel_hi:[1,0]
	v_pk_mul_f32 v[56:57], v[56:57], v[172:173] op_sel_hi:[1,0]
	v_pk_mul_f32 v[58:59], v[58:59], v[172:173] op_sel_hi:[1,0]
	v_pk_mul_f32 v[60:61], v[60:61], v[172:173] op_sel_hi:[1,0]
	v_pk_mul_f32 v[62:63], v[62:63], v[172:173] op_sel_hi:[1,0]
	v_max_f32_e32 v48, 0, v48
	v_max_f32_e32 v49, 0, v49
	v_max_f32_e32 v50, 0, v50
	v_max_f32_e32 v51, 0, v51
	v_max_f32_e32 v52, 0, v52
	v_max_f32_e32 v53, 0, v53
	v_max_f32_e32 v54, 0, v54
	v_max_f32_e32 v55, 0, v55
	v_max_f32_e32 v56, 0, v56
	v_max_f32_e32 v57, 0, v57
	v_max_f32_e32 v58, 0, v58
	v_max_f32_e32 v59, 0, v59
	v_max_f32_e32 v60, 0, v60
	v_max_f32_e32 v61, 0, v61
	v_max_f32_e32 v62, 0, v62
	v_max_f32_e32 v63, 0, v63
	v_pk_mul_f32 v[48:49], v[48:49], v[48:49]
	v_pk_mul_f32 v[50:51], v[50:51], v[50:51]
	v_pk_mul_f32 v[52:53], v[52:53], v[52:53]
	v_pk_mul_f32 v[54:55], v[54:55], v[54:55]
; __device__ __forceinline__ u32x4 pack8(const f32x4 a, const f32x4 b) { u32x4 w; w.x = cvt_pk_bf16(a[0], a[1]); w.y = cvt_pk_bf16(a[2], a[3]); w.z = cvt_pk_bf16(b[0], b[1]); w.w = cvt_pk_bf16(b[2], b[3]); return w; }
;     __device__ __forceinline__ void operator()(const f32x4 (&acc)[2][2][4][2], const Unit& u, int wr, int wc, int fr, int fq) const {
;     ...
;                 for (int bj = 0; bj < 2; ++bj) { f32x4 v0 = acc[ai][bj][m][0] * rstd, v1 = acc[ai][bj][m][1] * rstd;
; #pragma unroll
;                     for (int i = 0; i < 4; ++i) { const float a = fmaxf(v0[i], 0.f), b = fmaxf(v1[i], 0.f); v0[i] = a * a; v1[i] = b * b; }
;                     *(u32x4*)(Z + (size_t)row * FF + cb + bj * 128) = pack8(v0, v1); }
	v_pk_mul_f32 v[56:57], v[56:57], v[56:57]
	v_pk_mul_f32 v[58:59], v[58:59], v[58:59]
	v_pk_mul_f32 v[60:61], v[60:61], v[60:61]
	v_pk_mul_f32 v[62:63], v[62:63], v[62:63]
	v_cvt_pk_bf16_f32 v60, v60, v61
	v_cvt_pk_bf16_f32 v61, v62, v63
	v_cvt_pk_bf16_f32 v62, v56, v57
	v_cvt_pk_bf16_f32 v63, v58, v59
	v_cvt_pk_bf16_f32 v52, v52, v53
	v_cvt_pk_bf16_f32 v53, v54, v55
	v_cvt_pk_bf16_f32 v54, v48, v49
	v_cvt_pk_bf16_f32 v55, v50, v51
	global_store_dwordx4 v[220:221], v[60:63], off
	global_store_dwordx4 v[220:221], v[52:55], off offset:256
	v_lshl_add_u64 v[220:221], v[220:221], 0, s[98:99]
	v_pk_mul_f32 v[32:33], v[32:33], v[176:177] op_sel_hi:[1,0]
	v_pk_mul_f32 v[34:35], v[34:35], v[176:177] op_sel_hi:[1,0]
	v_pk_mul_f32 v[36:37], v[36:37], v[176:177] op_sel_hi:[1,0]
	v_pk_mul_f32 v[38:39], v[38:39], v[176:177] op_sel_hi:[1,0]
	v_pk_mul_f32 v[40:41], v[40:41], v[176:177] op_sel_hi:[1,0]
	v_pk_mul_f32 v[42:43], v[42:43], v[176:177] op_sel_hi:[1,0]
	v_pk_mul_f32 v[44:45], v[44:45], v[176:177] op_sel_hi:[1,0]
	v_pk_mul_f32 v[46:47], v[46:47], v[176:177] op_sel_hi:[1,0]
	v_max_f32_e32 v32, 0, v32
	v_max_f32_e32 v33, 0, v33
	v_max_f32_e32 v34, 0, v34
	v_max_f32_e32 v35, 0, v35
	v_max_f32_e32 v36, 0, v36
	v_max_f32_e32 v37, 0, v37
	v_max_f32_e32 v38, 0, v38
	v_max_f32_e32 v39, 0, v39
	v_max_f32_e32 v40, 0, v40
	v_max_f32_e32 v41, 0, v41
	v_max_f32_e32 v42, 0, v42
	v_max_f32_e32 v43, 0, v43
	v_max_f32_e32 v44, 0, v44
	v_max_f32_e32 v45, 0, v45
	v_max_f32_e32 v46, 0, v46
	v_max_f32_e32 v47, 0, v47
	v_pk_mul_f32 v[32:33], v[32:33], v[32:33]
	v_pk_mul_f32 v[34:35], v[34:35], v[34:35]
	v_pk_mul_f32 v[36:37], v[36:37], v[36:37]
	v_pk_mul_f32 v[38:39], v[38:39], v[38:39]
	v_pk_mul_f32 v[40:41], v[40:41], v[40:41]
	v_pk_mul_f32 v[42:43], v[42:43], v[42:43]
	v_pk_mul_f32 v[44:45], v[44:45], v[44:45]
	v_pk_mul_f32 v[46:47], v[46:47], v[46:47]
	v_cvt_pk_bf16_f32 v44, v44, v45
	v_cvt_pk_bf16_f32 v45, v46, v47
	v_cvt_pk_bf16_f32 v46, v40, v41
	v_cvt_pk_bf16_f32 v47, v42, v43
	v_cvt_pk_bf16_f32 v36, v36, v37
	v_cvt_pk_bf16_f32 v37, v38, v39
	v_cvt_pk_bf16_f32 v38, v32, v33
	v_cvt_pk_bf16_f32 v39, v34, v35
	global_store_dwordx4 v[220:221], v[44:47], off
	global_store_dwordx4 v[220:221], v[36:39], off offset:256
	v_lshl_add_u64 v[220:221], v[220:221], 0, s[98:99]
	v_pk_mul_f32 v[16:17], v[16:17], v[180:181] op_sel_hi:[1,0]
	v_pk_mul_f32 v[18:19], v[18:19], v[180:181] op_sel_hi:[1,0]
	v_pk_mul_f32 v[20:21], v[20:21], v[180:181] op_sel_hi:[1,0]
	v_pk_mul_f32 v[22:23], v[22:23], v[180:181] op_sel_hi:[1,0]
	v_pk_mul_f32 v[24:25], v[24:25], v[180:181] op_sel_hi:[1,0]
	v_pk_mul_f32 v[26:27], v[26:27], v[180:181] op_sel_hi:[1,0]
	v_pk_mul_f32 v[28:29], v[28:29], v[180:181] op_sel_hi:[1,0]
	v_pk_mul_f32 v[30:31], v[30:31], v[180:181] op_sel_hi:[1,0]
	v_max_f32_e32 v16, 0, v16
	v_max_f32_e32 v17, 0, v17
	v_max_f32_e32 v18, 0, v18
	v_max_f32_e32 v19, 0, v19
	v_max_f32_e32 v20, 0, v20
	v_max_f32_e32 v21, 0, v21
	v_max_f32_e32 v22, 0, v22
	v_max_f32_e32 v23, 0, v23
	v_max_f32_e32 v24, 0, v24
	v_max_f32_e32 v25, 0, v25
	v_max_f32_e32 v26, 0, v26
	v_max_f32_e32 v27, 0, v27
	v_max_f32_e32 v28, 0, v28
	v_max_f32_e32 v29, 0, v29
	v_max_f32_e32 v30, 0, v30
	v_max_f32_e32 v31, 0, v31
	v_pk_mul_f32 v[16:17], v[16:17], v[16:17]
	v_pk_mul_f32 v[18:19], v[18:19], v[18:19]
	v_pk_mul_f32 v[20:21], v[20:21], v[20:21]
	v_pk_mul_f32 v[22:23], v[22:23], v[22:23]
	v_pk_mul_f32 v[24:25], v[24:25], v[24:25]
	v_pk_mul_f32 v[26:27], v[26:27], v[26:27]
	v_pk_mul_f32 v[28:29], v[28:29], v[28:29]
	v_pk_mul_f32 v[30:31], v[30:31], v[30:31]
	v_cvt_pk_bf16_f32 v28, v28, v29
	v_cvt_pk_bf16_f32 v29, v30, v31
	v_cvt_pk_bf16_f32 v30, v24, v25
	v_cvt_pk_bf16_f32 v31, v26, v27
	v_cvt_pk_bf16_f32 v20, v20, v21
	v_cvt_pk_bf16_f32 v21, v22, v23
	v_cvt_pk_bf16_f32 v22, v16, v17
	v_cvt_pk_bf16_f32 v23, v18, v19
	global_store_dwordx4 v[220:221], v[28:31], off
	global_store_dwordx4 v[220:221], v[20:23], off offset:256
	v_lshl_add_u64 v[220:221], v[220:221], 0, s[98:99]
	v_pk_mul_f32 v[0:1], v[0:1], v[184:185] op_sel_hi:[1,0]
	v_pk_mul_f32 v[2:3], v[2:3], v[184:185] op_sel_hi:[1,0]
	v_pk_mul_f32 v[4:5], v[4:5], v[184:185] op_sel_hi:[1,0]
	v_pk_mul_f32 v[6:7], v[6:7], v[184:185] op_sel_hi:[1,0]
	v_pk_mul_f32 v[8:9], v[8:9], v[184:185] op_sel_hi:[1,0]
	v_pk_mul_f32 v[10:11], v[10:11], v[184:185] op_sel_hi:[1,0]
	v_pk_mul_f32 v[12:13], v[12:13], v[184:185] op_sel_hi:[1,0]
	v_pk_mul_f32 v[14:15], v[14:15], v[184:185] op_sel_hi:[1,0]
	v_max_f32_e32 v0, 0, v0
	v_max_f32_e32 v1, 0, v1
	v_max_f32_e32 v2, 0, v2
	v_max_f32_e32 v3, 0, v3
	v_max_f32_e32 v4, 0, v4
	v_max_f32_e32 v5, 0, v5
	v_max_f32_e32 v6, 0, v6
	v_max_f32_e32 v7, 0, v7
	v_max_f32_e32 v8, 0, v8
	v_max_f32_e32 v9, 0, v9
	v_max_f32_e32 v10, 0, v10
	v_max_f32_e32 v11, 0, v11
	v_max_f32_e32 v12, 0, v12
	v_max_f32_e32 v13, 0, v13
	v_max_f32_e32 v14, 0, v14
	v_max_f32_e32 v15, 0, v15
	v_pk_mul_f32 v[0:1], v[0:1], v[0:1]
	v_pk_mul_f32 v[2:3], v[2:3], v[2:3]
	v_pk_mul_f32 v[4:5], v[4:5], v[4:5]
	v_pk_mul_f32 v[6:7], v[6:7], v[6:7]
	v_pk_mul_f32 v[8:9], v[8:9], v[8:9]
	v_pk_mul_f32 v[10:11], v[10:11], v[10:11]
	v_pk_mul_f32 v[12:13], v[12:13], v[12:13]
	v_pk_mul_f32 v[14:15], v[14:15], v[14:15]
	v_cvt_pk_bf16_f32 v12, v12, v13
	v_cvt_pk_bf16_f32 v13, v14, v15
	v_cvt_pk_bf16_f32 v14, v8, v9
	v_cvt_pk_bf16_f32 v15, v10, v11
	v_cvt_pk_bf16_f32 v4, v4, v5
	v_cvt_pk_bf16_f32 v5, v6, v7
	v_cvt_pk_bf16_f32 v6, v0, v1
	v_cvt_pk_bf16_f32 v7, v2, v3
	global_store_dwordx4 v[220:221], v[12:15], off
	global_store_dwordx4 v[220:221], v[4:7], off offset:256
	s_andn2_b64 vcc, exec, s[4:5]
	s_mov_b64 s[4:5], -1
	s_cbranch_vccnz .LBB0_1536
	s_andn2_b64 vcc, exec, s[6:7]
	s_cbranch_vccnz .LBB0_1535
	s_barrier
	s_branch .LBB0_1535
